# attention loop: K/V LDS-DMA addressing via uniform SGPR bases (s[0:1], s[90:91]) + constant 32-bit lane offsets instead of 64-bit per-lane pointers: the six v_lshl_add_u64 per iteration become four SA
# speedup vs baseline: 1.0022x; 1.0022x over previous
; #define SBAR() __builtin_amdgcn_sched_barrier(0)
; #define KRD(d0) do { if constexpr (VAR & 4) break; const char* a_ = Kc + (((2 * (d0) + hi) ^ sw) << 4); ka[d0] = *reinterpret_cast<const bf16x8*>(a_); kb[d0] = *reinterpret_cast<const bf16x8*>(a_ + 32 * 128); } while (0)
; #define SUM4(Y, b) do { if constexpr (!(VAR & 8)) { ps += (Y[b] + Y[(b) + 1]) + (Y[(b) + 2] + Y[(b) + 3]); asm volatile("" : "+v"(ps)); } } while (0)
; #define PKA(Y, b) do { if constexpr (!(VAR & 8)) { a0 = cvtpk(Y[b], Y[(b) + 1]); a1 = cvtpk(Y[(b) + 2], Y[(b) + 3]); } } while (0)
; #define PKB(Y, b, OUT) do { if constexpr (VAR & 8) { OUT = ka[0]; asm volatile("" : "+v"(OUT)); } else { b0 = cvtpk(Y[b], Y[(b) + 1]); b1 = cvtpk(Y[(b) + 2], Y[(b) + 3]); u32x4 w_ = {a0, a1, b0, b1}; OUT = *reinterpret_cast<bf16x8*>(&w_); asm volatile("" : "+v"(OUT)); } } while (0)
; #define QKM(X, KF, QF, C) do { if constexpr (VAR & 4) { X = C; asm volatile("" : "+v"(X)); } else X = __builtin_amdgcn_mfma_f32_32x32x16_bf16(KF, QF, C, 0, 0, 0); } while (0)
; template <int VAR> ...
;     ...
;     ka[0] = kp[0]; kb[0] = kp[1]; ka[1] = kp[2]; kb[1] = kp[3]; if (dk) glds16(gk, lk); SBAR();
;     { const f32x16 z = f32x16{};
;       QKM(x0, ka[0], qr[0], z);  SUM4(y0, 0); PKA(y0, 0);       SBAR();
;       QKM(x1, kb[0], qr[0], z);  SUM4(y0, 4); PKB(y0, 4, pa0);  KRD(2); if (dv) glds16(gv, lv); SBAR(); }
;     QKM(x0, ka[1], qr[1], x0); SUM4(y0, 8); PKA(y0, 8);       SBAR();
;     QKM(x1, kb[1], qr[1], x1); SUM4(y0, 12); PKB(y0, 12, pa1); KRD(3); if (dv) glds16(gv + 8192, lv + 8192); SBAR();
; template <int VAR>
; __device__ __forceinline__ void dattn_block(const BlockRef& cur, const BlockRef& nxt, bool has_next, char* lds, Seam& S, const Outs& OU) {
;     ...
;     bf16x8 kp[4];
;     { const char* a0_ = Kl + s_cur * SHM_K + (((0 + hi) ^ sw) << 4); const char* a1_ = Kl + s_cur * SHM_K + (((2 + hi) ^ sw) << 4);
;       kp[0] = *reinterpret_cast<const bf16x8*>(a0_); kp[1] = *reinterpret_cast<const bf16x8*>(a0_ + 32 * 128); kp[2] = *reinterpret_cast<const bf16x8*>(a1_); kp[3] = *reinterpret_cast<const bf16x8*>(a1_ + 32 * 128); }
;     ...
;     const int TL1 = __builtin_amdgcn_readfirstlane((qlo + 31) / KVBLK + 1);
;     int t = 1;
;     for (; t + 1 < TL1; t += 2) { STEP(pB0, pB1, pA0, pA1, t); STEP(pA0, pA1, pB0, pB1, t + 1); }
.LBB0_354:
	s_waitcnt vmcnt(0) lgkmcnt(0)
	s_barrier
	s_add_i32 s0, s80, 0x10f
	ds_read_b128 v[174:177], v222 offset:57344
	ds_read_b128 v[170:173], v222 offset:61440
	ds_read_b128 v[166:169], v223 offset:57344
	ds_read_b128 v[162:165], v223 offset:61440
	s_lshr_b32 s84, s0, 6
	s_add_i32 s0, s62, 31
	s_ashr_i32 s1, s0, 31
	v_exp_f32_e32 v82, v36
	v_exp_f32_e32 v83, v37
	v_exp_f32_e32 v84, v38
	v_exp_f32_e32 v85, v39
	v_exp_f32_e32 v86, v40
	v_exp_f32_e32 v87, v41
	v_exp_f32_e32 v88, v42
	v_exp_f32_e32 v89, v43
	v_exp_f32_e32 v90, v44
	v_exp_f32_e32 v91, v45
	v_exp_f32_e32 v92, v46
	v_exp_f32_e32 v93, v47
	v_exp_f32_e32 v94, v48
	v_exp_f32_e32 v95, v49
	v_exp_f32_e32 v96, v50
	v_exp_f32_e32 v97, v51
	v_exp_f32_e32 v98, v54
	v_exp_f32_e32 v99, v55
	v_exp_f32_e32 v100, v52
	v_exp_f32_e32 v101, v53
	v_exp_f32_e32 v102, v58
	v_exp_f32_e32 v103, v59
	v_exp_f32_e32 v104, v56
	v_exp_f32_e32 v105, v57
	v_exp_f32_e32 v106, v64
	v_exp_f32_e32 v107, v65
	v_exp_f32_e32 v108, v62
	v_exp_f32_e32 v109, v63
	v_exp_f32_e32 v110, v60
	v_exp_f32_e32 v111, v61
	v_exp_f32_e32 v112, v3
	v_exp_f32_e32 v113, v66
	s_lshr_b32 s1, s1, 26
	s_add_i32 s0, s0, s1
	s_andn2_b64 vcc, exec, s[4:5]
	s_ashr_i32 s60, s0, 6
	s_cmpk_lt_i32 s62, 0x61
	s_cbranch_scc1 .LBB0_402
	s_lshl_b32 s87, s81, 10
	s_cmp_lg_u32 0, -1
	s_cselect_b32 s0, 0, 0
	s_add_i32 s87, s87, s0
	s_lshl_b32 s0, s20, 10
	s_add_i32 s0, s63, s0
	s_lshl_b32 s1, s81, 7
	v_lshl_add_u64 v[4:5], s[18:19], 0, v[198:199]
	v_mov_b32_e32 v227, 0
	s_add_i32 s0, s0, s1
	s_mov_b32 s67, 0
	s_add_i32 s88, s87, 0xc000
	v_cmp_neq_f32_e64 s[4:5], 0, v204
	v_add_u32_e32 v3, s0, v220
	v_lshl_add_u64 v[206:207], v[4:5], 0, s[40:41]
	s_movk_i32 s2, 0x2000
	s_movk_i32 s89, 0x80
	s_mov_b32 s20, 2
	v_mov_b64_e32 v[208:209], v[202:203]
	s_movk_i32 s86, 0x4000
	v_mov_b32_e32 v66, 0
	v_mov_b32_e32 v67, v227
	v_mov_b32_e32 v68, v227
	v_mov_b32_e32 v69, v227
	v_mov_b32_e32 v70, v227
	v_mov_b32_e32 v71, v227
	v_mov_b32_e32 v72, v227
	v_mov_b32_e32 v73, v227
	v_mov_b32_e32 v74, v227
	v_mov_b32_e32 v75, v227
	v_mov_b32_e32 v76, v227
	v_mov_b32_e32 v77, v227
	v_mov_b32_e32 v78, v227
	v_mov_b32_e32 v79, v227
	v_mov_b32_e32 v80, v227
	v_mov_b32_e32 v81, v227
	v_mov_b32_e32 v50, 0
	v_mov_b32_e32 v51, v227
	v_mov_b32_e32 v52, v227
	v_mov_b32_e32 v53, v227
	v_mov_b32_e32 v54, v227
	v_mov_b32_e32 v55, v227
	v_mov_b32_e32 v56, v227
	v_mov_b32_e32 v57, v227
	v_mov_b32_e32 v58, v227
	v_mov_b32_e32 v59, v227
	v_mov_b32_e32 v60, v227
	v_mov_b32_e32 v61, v227
	v_mov_b32_e32 v62, v227
	v_mov_b32_e32 v63, v227
	v_mov_b32_e32 v64, v227
	v_mov_b32_e32 v65, v227
	v_mov_b32_e32 v34, 0
	v_mov_b32_e32 v35, v227
	v_mov_b32_e32 v36, v227
	v_mov_b32_e32 v37, v227
	v_mov_b32_e32 v38, v227
	v_mov_b32_e32 v39, v227
	v_mov_b32_e32 v40, v227
	v_mov_b32_e32 v41, v227
	v_mov_b32_e32 v42, v227
	v_mov_b32_e32 v43, v227
	v_mov_b32_e32 v44, v227
	v_mov_b32_e32 v45, v227
	v_mov_b32_e32 v46, v227
	v_mov_b32_e32 v47, v227
	v_mov_b32_e32 v48, v227
	v_mov_b32_e32 v49, v227
	v_mov_b32_e32 v18, 0
	v_mov_b32_e32 v19, v227
	v_mov_b32_e32 v20, v227
	v_mov_b32_e32 v21, v227
	v_mov_b32_e32 v22, v227
	v_mov_b32_e32 v23, v227
	v_mov_b32_e32 v24, v227
	v_mov_b32_e32 v25, v227
	v_mov_b32_e32 v26, v227
	v_mov_b32_e32 v27, v227
	v_mov_b32_e32 v28, v227
	v_mov_b32_e32 v29, v227
	v_mov_b32_e32 v30, v227
	v_mov_b32_e32 v31, v227
	v_mov_b32_e32 v32, v227
	v_mov_b32_e32 v33, v227
	s_cmp_lg_u64 s[4:5], 0
	s_cselect_b32 s100, 0x80000000, s85
	s_add_i32 s101, s100, 64
	v_add_u32_e32 v237, v215, v216
	v_add_u32_e32 v238, v215, v217
	v_add_u32_e32 v239, v215, v218
	v_add_u32_e32 v240, v215, v219
	v_add_u32_e32 v241, 0x2000, v198
	v_add_u32_e32 v242, 0x4000, v198
	v_add_u32_e32 v243, 0x6000, v198
	v_readfirstlane_b32 s92, v198
	v_readfirstlane_b32 s0, v206
	v_readfirstlane_b32 s1, v207
	v_readfirstlane_b32 s90, v208
	v_readfirstlane_b32 s91, v209
	s_sub_u32 s90, s90, s92
	s_subb_u32 s91, s91, 0
	s_add_u32 s92, s92, 0x2000
	s_sub_u32 s0, s0, s92
	s_subb_u32 s1, s1, 0
.LBB0_356:
	s_add_i32 s62, s20, 1
	s_add_i32 m0, s67, s88
	s_lshl1_add_u32 s66, s86, s87
	global_load_lds_dwordx4 v198, s[0:1]
	s_waitcnt lgkmcnt(2)
	v_mfma_f32_32x32x16_bf16 v[130:145], v[174:177], v[146:149], 0
	v_add_f32_e32 v4, v82, v83
	v_add_f32_e32 v5, v84, v85
	v_add_f32_e32 v6, v4, v5
	v_cvt_pk_bf16_f32 v4, v82, v83
	v_cvt_pk_bf16_f32 v5, v84, v85
	v_add_f32_e32 v7, v86, v87
	v_add_f32_e32 v8, v88, v89
	v_mfma_f32_32x32x16_bf16 v[114:129], v[170:173], v[146:149], 0
	v_add_f32_e32 v7, v7, v8
	v_add_f32_e32 v8, v7, v6
	v_cvt_pk_bf16_f32 v6, v86, v87
	v_cvt_pk_bf16_f32 v7, v88, v89
	v_add_u32_e32 v9, s2, v239
	s_mov_b32 m0, s66
	ds_read_b128 v[14:17], v9 offset:49152
	ds_read_b128 v[86:89], v9 offset:53248
	global_load_lds_dwordx4 v198, s[90:91]
	s_waitcnt lgkmcnt(2)
	v_mfma_f32_32x32x16_bf16 v[130:145], v[166:169], v[150:153], v[130:145]
	v_add_f32_e32 v9, v90, v91
	v_add_f32_e32 v10, v92, v93
	v_add_f32_e32 v9, v9, v10
	v_add_f32_e32 v10, v9, v8
	v_cvt_pk_bf16_f32 v8, v90, v91
	v_cvt_pk_bf16_f32 v9, v92, v93
	v_add_f32_e32 v11, v94, v95
	v_add_f32_e32 v13, v96, v97
	v_mfma_f32_32x32x16_bf16 v[114:129], v[162:165], v[150:153], v[114:129]
	v_add_f32_e32 v11, v11, v13
	v_add_f32_e32 v13, v11, v10
	v_cvt_pk_bf16_f32 v10, v94, v95
	v_cvt_pk_bf16_f32 v11, v96, v97
	v_add_u32_e32 v12, s2, v240
	ds_read_b128 v[90:93], v12 offset:49152
	ds_read_b128 v[82:85], v12 offset:53248
	s_add_i32 m0, s66, 0x2000
	s_cmp_le_i32 s89, s101
	global_load_lds_dwordx4 v241, s[90:91]
	s_waitcnt lgkmcnt(2)
	v_mfma_f32_32x32x16_bf16 v[130:145], v[14:17], v[154:157], v[130:145]
	v_add_f32_e32 v12, v98, v99
	v_add_f32_e32 v94, v100, v101
	v_add_f32_e32 v12, v12, v94
	v_add_f32_e32 v94, v12, v13
	v_cvt_pk_bf16_f32 v12, v98, v99
	v_cvt_pk_bf16_f32 v13, v100, v101
	v_mfma_f32_32x32x16_bf16 v[114:129], v[86:89], v[154:157], v[114:129]
	v_add_f32_e32 v14, v102, v103
	v_add_f32_e32 v15, v104, v105
	v_add_f32_e32 v14, v14, v15
	v_add_f32_e32 v16, v14, v94
	v_cvt_pk_bf16_f32 v14, v102, v103
	v_cvt_pk_bf16_f32 v15, v104, v105
	s_waitcnt lgkmcnt(0)
	v_mfma_f32_32x32x16_bf16 v[130:145], v[90:93], v[158:161], v[130:145]
	v_add_f32_e32 v17, v106, v107
	v_add_f32_e32 v86, v108, v109
	v_add_f32_e32 v17, v17, v86
	v_add_f32_e32 v16, v17, v16
	v_cvt_pk_bf16_f32 v178, v106, v107
	v_cvt_pk_bf16_f32 v179, v108, v109
	v_add_f32_e32 v17, v110, v111
	v_add_f32_e32 v86, v112, v113
	v_add_f32_e32 v17, v17, v86
	v_add_f32_e32 v229, v17, v16
	v_cvt_pk_bf16_f32 v180, v110, v111
	v_cvt_pk_bf16_f32 v181, v112, v113
	v_lshl_add_u32 v16, s67, 1, v214
	v_mfma_f32_32x32x16_bf16 v[114:129], v[82:85], v[158:161], v[114:129]
	ds_read_b64_tr_b16 v[174:175], v16
	ds_read_b64_tr_b16 v[176:177], v16 offset:256
	ds_read_b64_tr_b16 v[170:171], v16 offset:4096
	ds_read_b64_tr_b16 v[172:173], v16 offset:4352
	ds_read_b64_tr_b16 v[166:167], v16 offset:8192
	ds_read_b64_tr_b16 v[168:169], v16 offset:8448
	ds_read_b64_tr_b16 v[162:163], v16 offset:12288
	ds_read_b64_tr_b16 v[164:165], v16 offset:12544
	s_cbranch_scc0 .Lp2s_disp1
; #define SBAR() __builtin_amdgcn_sched_barrier(0)
; template <int VAR> ...
;     ...
;     float ps = 0.f;
;     if constexpr (VAR & 4) { ka[0] = qr[0]; ka[1] = qr[1]; ka[2] = qr[2]; ka[3] = qr[3]; kb[0] = qr[0]; kb[1] = qr[1]; kb[2] = qr[2]; kb[3] = qr[3]; }
;     ka[0] = kp[0]; kb[0] = kp[1]; ka[1] = kp[2]; kb[1] = kp[3]; if (dk) glds16(gk, lk); SBAR();
;     { const f32x16 z = f32x16{};
;       QKM(x0, ka[0], qr[0], z);  SUM4(y0, 0); PKA(y0, 0);       SBAR();
;       QKM(x1, kb[0], qr[0], z);  SUM4(y0, 4); PKB(y0, 4, pa0);  KRD(2); if (dv) glds16(gv, lv); SBAR(); }
;     QKM(x0, ka[1], qr[1], x0); SUM4(y0, 8); PKA(y0, 8);       SBAR();
;     QKM(x1, kb[1], qr[1], x1); SUM4(y0, 12); PKB(y0, 12, pa1); KRD(3); if (dv) glds16(gv + 8192, lv + 8192); SBAR();
;     QKM(x0, ka[2], qr[2], x0); SUM4(y1, 0); PKA(y1, 0);       SBAR();
;     QKM(x1, kb[2], qr[2], x1); SUM4(y1, 4); PKB(y1, 4, pa2);  SBAR();
;     QKM(x0, ka[3], qr[3], x0); SUM4(y1, 8); PKA(y1, 8);       SBAR();
;     QKM(x1, kb[3], qr[3], x1); SUM4(y1, 12); PKB(y1, 12, pa3); VRD(0); VRD(1); SBAR();
;     VRD(2); VRD(3); SBAR();
;     if (near) {
;         float tA[4], uA[4], tB[4], uB[4];
;     ...
;         TLD(tA, uA, 0); SBAR(); TLD(tB, uB, 1); SBAR();
;         asm volatile("s_nop 15\n\ts_nop 7" : "+v"(x0), "+v"(x1));
;         TAD(tA, uA, 0); SBAR(); TLD(tA, uA, 2); SBAR(); TAD(tB, uB, 1); SBAR(); TLD(tB, uB, 3); SBAR(); TAD(tA, uA, 2); SBAR(); TAD(tB, uB, 3);
;     ...
;     } else if (__builtin_expect(shift != 0.f, 0)) {
;         asm volatile("s_nop 15\n\ts_nop 7" : "+v"(x0), "+v"(x1));
; #pragma unroll
;         for (int r = 0; r < 16; ++r) { asm volatile("v_sub_f32 %0, %0, %1" : "+v"(x0[r]) : "v"(shift)); asm volatile("v_sub_f32 %0, %0, %1" : "+v"(x1[r]) : "v"(shift)); }
;     }
;     SBAR();
;     ...
;     GAPB(0, pa0); GAPB(1, pa1); GAPB(2, pa2); GAPB(3, pa3); GAPB(4, pa0); GAPB(5, pa1); GAPB(6, pa2); GAPB(7, pa3);
;     GAPB(8, pa0); GAPB(9, pa1); GAPB(10, pa2); GAPB(11, pa3);
;     if (wv == 3) asm volatile("s_waitcnt vmcnt(3)" ::: "memory"); else if (wv == 2) asm volatile("s_waitcnt vmcnt(2)" ::: "memory"); else asm volatile("s_waitcnt vmcnt(0)" ::: "memory");
;     asm volatile("s_waitcnt lgkmcnt(0)\n\ts_barrier" ::: "memory");
;     if (pre) { const char* a0_ = Kn + (((0 + hi) ^ sw) << 4); const char* a1_ = Kn + (((2 + hi) ^ sw) << 4);
.LBB0_367:
	s_waitcnt lgkmcnt(4)
	v_mfma_f32_32x32x16_bf16 v[66:81], v[4:7], v[174:177], v[66:81]
	v_exp_f32_e32 v130, v130
	v_exp_f32_e32 v114, v114
	ds_read_b64_tr_b16 v[98:99], v16 offset:512
	ds_read_b64_tr_b16 v[100:101], v16 offset:768
	v_mfma_f32_32x32x16_bf16 v[66:81], v[8:11], v[170:173], v[66:81]
	v_exp_f32_e32 v131, v131
	v_exp_f32_e32 v115, v115
	ds_read_b64_tr_b16 v[102:103], v16 offset:4608
	ds_read_b64_tr_b16 v[104:105], v16 offset:4864
	s_waitcnt lgkmcnt(4)
	v_mfma_f32_32x32x16_bf16 v[66:81], v[12:15], v[166:169], v[66:81]
	v_exp_f32_e32 v132, v132
	v_exp_f32_e32 v116, v116
	ds_read_b64_tr_b16 v[106:107], v16 offset:8704
	ds_read_b64_tr_b16 v[108:109], v16 offset:8960
	v_mfma_f32_32x32x16_bf16 v[66:81], v[178:181], v[162:165], v[66:81]
	v_exp_f32_e32 v133, v133
	v_exp_f32_e32 v117, v117
	ds_read_b64_tr_b16 v[110:111], v16 offset:12800
	ds_read_b64_tr_b16 v[112:113], v16 offset:13056
	s_waitcnt lgkmcnt(4)
	v_mfma_f32_32x32x16_bf16 v[50:65], v[4:7], v[98:101], v[50:65]
	v_exp_f32_e32 v134, v134
	v_exp_f32_e32 v118, v118
	v_exp_f32_e32 v142, v142
	ds_read_b64_tr_b16 v[82:83], v16 offset:1024
	ds_read_b64_tr_b16 v[84:85], v16 offset:1280
	v_mfma_f32_32x32x16_bf16 v[50:65], v[8:11], v[102:105], v[50:65]
	v_exp_f32_e32 v135, v135
	v_exp_f32_e32 v119, v119
	v_exp_f32_e32 v126, v126
	ds_read_b64_tr_b16 v[86:87], v16 offset:5120
	ds_read_b64_tr_b16 v[88:89], v16 offset:5376
	s_waitcnt lgkmcnt(4)
	v_mfma_f32_32x32x16_bf16 v[50:65], v[12:15], v[106:109], v[50:65]
	v_exp_f32_e32 v136, v136
	v_exp_f32_e32 v120, v120
	v_exp_f32_e32 v143, v143
	ds_read_b64_tr_b16 v[90:91], v16 offset:9216
	ds_read_b64_tr_b16 v[92:93], v16 offset:9472
	v_mfma_f32_32x32x16_bf16 v[50:65], v[178:181], v[110:113], v[50:65]
	v_exp_f32_e32 v137, v137
	v_exp_f32_e32 v121, v121
	v_exp_f32_e32 v127, v127
	ds_read_b64_tr_b16 v[94:95], v16 offset:13312
	ds_read_b64_tr_b16 v[96:97], v16 offset:13568
	s_waitcnt lgkmcnt(4)
	v_mfma_f32_32x32x16_bf16 v[34:49], v[4:7], v[82:85], v[34:49]
	v_exp_f32_e32 v138, v138
	v_exp_f32_e32 v122, v122
	v_exp_f32_e32 v144, v144
	ds_read_b64_tr_b16 v[98:99], v16 offset:1536
	ds_read_b64_tr_b16 v[100:101], v16 offset:1792
	v_mfma_f32_32x32x16_bf16 v[34:49], v[8:11], v[86:89], v[34:49]
	v_exp_f32_e32 v139, v139
	v_exp_f32_e32 v123, v123
	v_exp_f32_e32 v128, v128
	ds_read_b64_tr_b16 v[102:103], v16 offset:5632
	ds_read_b64_tr_b16 v[104:105], v16 offset:5888
	s_waitcnt lgkmcnt(4)
	v_mfma_f32_32x32x16_bf16 v[34:49], v[12:15], v[90:93], v[34:49]
	v_exp_f32_e32 v140, v140
	v_exp_f32_e32 v124, v124
	v_exp_f32_e32 v145, v145
	ds_read_b64_tr_b16 v[106:107], v16 offset:9728
	ds_read_b64_tr_b16 v[108:109], v16 offset:9984
	v_mfma_f32_32x32x16_bf16 v[34:49], v[178:181], v[94:97], v[34:49]
	v_exp_f32_e32 v141, v141
	v_exp_f32_e32 v125, v125
	v_exp_f32_e32 v129, v129
	ds_read_b64_tr_b16 v[110:111], v16 offset:13824
	ds_read_b64_tr_b16 v[112:113], v16 offset:14080
	s_waitcnt vmcnt(3) lgkmcnt(0)
	s_barrier
	v_add_u32_e32 v16, s86, v237
	v_add_u32_e32 v17, s86, v238
	ds_read_b128 v[174:177], v16 offset:49152
	ds_read_b128 v[170:173], v16 offset:53248
	ds_read_b128 v[166:169], v17 offset:49152
	ds_read_b128 v[162:165], v17 offset:53248
	v_mfma_f32_32x32x16_bf16 v[18:33], v[4:7], v[98:101], v[18:33]
	v_mfma_f32_32x32x16_bf16 v[18:33], v[8:11], v[102:105], v[18:33]
	v_mfma_f32_32x32x16_bf16 v[18:33], v[12:15], v[106:109], v[18:33]
	v_mfma_f32_32x32x16_bf16 v[18:33], v[178:181], v[110:113], v[18:33]
	s_add_i32 s92, s86, 0x2000
	s_cmp_lg_u32 s86, 0x4000
	s_cselect_b32 s68, s92, 0
	s_add_i32 s20, s20, 2
	s_add_i32 m0, s2, s88
	s_lshl1_add_u32 s69, s68, s87
	global_load_lds_dwordx4 v241, s[0:1]
	s_waitcnt lgkmcnt(2)
	v_mfma_f32_32x32x16_bf16 v[82:97], v[174:177], v[146:149], 0
	v_add_f32_e32 v4, v130, v131
	v_add_f32_e32 v5, v132, v133
	v_add_f32_e32 v6, v4, v5
	v_cvt_pk_bf16_f32 v4, v130, v131
	v_cvt_pk_bf16_f32 v5, v132, v133
	v_add_f32_e32 v7, v134, v135
	v_add_f32_e32 v8, v136, v137
	v_mfma_f32_32x32x16_bf16 v[98:113], v[170:173], v[146:149], 0
	v_add_f32_e32 v7, v7, v8
	v_add_f32_e32 v8, v7, v6
	v_cvt_pk_bf16_f32 v6, v134, v135
	v_cvt_pk_bf16_f32 v7, v136, v137
	v_add_u32_e32 v9, s86, v239
	s_mov_b32 m0, s69
	ds_read_b128 v[14:17], v9 offset:49152
	ds_read_b128 v[130:133], v9 offset:53248
	global_load_lds_dwordx4 v242, s[90:91]
	s_waitcnt lgkmcnt(2)
	v_mfma_f32_32x32x16_bf16 v[82:97], v[166:169], v[150:153], v[82:97]
	v_add_f32_e32 v9, v138, v139
	v_add_f32_e32 v10, v140, v141
	v_add_f32_e32 v9, v9, v10
	v_add_f32_e32 v10, v9, v8
	v_cvt_pk_bf16_f32 v8, v138, v139
	v_cvt_pk_bf16_f32 v9, v140, v141
	v_add_f32_e32 v11, v142, v143
	v_add_f32_e32 v134, v144, v145
	v_mfma_f32_32x32x16_bf16 v[98:113], v[162:165], v[150:153], v[98:113]
	v_add_f32_e32 v11, v11, v134
	v_add_f32_e32 v178, v11, v10
	v_cvt_pk_bf16_f32 v10, v142, v143
	v_cvt_pk_bf16_f32 v11, v144, v145
	v_add_u32_e32 v134, s86, v240
	ds_read_b128 v[138:141], v134 offset:49152
	ds_read_b128 v[134:137], v134 offset:53248
	s_add_i32 m0, s69, 0x2000
	s_cmp_le_i32 s89, s100
	global_load_lds_dwordx4 v243, s[90:91]
	s_waitcnt lgkmcnt(2)
	v_mfma_f32_32x32x16_bf16 v[82:97], v[14:17], v[154:157], v[82:97]
	v_add_f32_e32 v12, v114, v115
	v_add_f32_e32 v13, v116, v117
	v_add_f32_e32 v12, v12, v13
	v_add_f32_e32 v142, v12, v178
	v_cvt_pk_bf16_f32 v12, v114, v115
	v_cvt_pk_bf16_f32 v13, v116, v117
	v_mfma_f32_32x32x16_bf16 v[98:113], v[130:133], v[154:157], v[98:113]
	v_add_f32_e32 v14, v118, v119
	v_add_f32_e32 v15, v120, v121
	v_add_f32_e32 v14, v14, v15
	v_add_f32_e32 v16, v14, v142
	v_cvt_pk_bf16_f32 v14, v118, v119
	v_cvt_pk_bf16_f32 v15, v120, v121
	s_waitcnt lgkmcnt(0)
	v_mfma_f32_32x32x16_bf16 v[82:97], v[138:141], v[158:161], v[82:97]
	v_add_f32_e32 v17, v122, v123
	v_add_f32_e32 v130, v124, v125
	v_add_f32_e32 v17, v17, v130
	v_add_f32_e32 v16, v17, v16
	v_cvt_pk_bf16_f32 v178, v122, v123
	v_cvt_pk_bf16_f32 v179, v124, v125
	v_add_f32_e32 v17, v126, v127
	v_add_f32_e32 v130, v128, v129
	v_add_f32_e32 v17, v17, v130
	v_add_f32_e32 v16, v17, v16
	v_cvt_pk_bf16_f32 v180, v126, v127
	v_cvt_pk_bf16_f32 v181, v128, v129
	v_lshl_add_u32 v17, s2, 1, v214
	v_mfma_f32_32x32x16_bf16 v[98:113], v[134:137], v[158:161], v[98:113]
	ds_read_b64_tr_b16 v[194:195], v17
	ds_read_b64_tr_b16 v[196:197], v17 offset:256
	ds_read_b64_tr_b16 v[190:191], v17 offset:4096
	ds_read_b64_tr_b16 v[192:193], v17 offset:4352
	ds_read_b64_tr_b16 v[186:187], v17 offset:8192
	ds_read_b64_tr_b16 v[188:189], v17 offset:8448
	ds_read_b64_tr_b16 v[182:183], v17 offset:12288
	ds_read_b64_tr_b16 v[184:185], v17 offset:12544
	s_cbranch_scc0 .Lp2s_disp2

; template <int VAR>
; __device__ __forceinline__ void dattn_block(const BlockRef& cur, const BlockRef& nxt, bool has_next, char* lds, Seam& S, const Outs& OU) {
;     ...
;     const int TL1 = __builtin_amdgcn_readfirstlane((qlo + 31) / KVBLK + 1);
;     int t = 1;
;     for (; t + 1 < TL1; t += 2) { STEP(pB0, pB1, pA0, pA1, t); STEP(pA0, pA1, pB0, pB1, t + 1); }
.LBB0_394:
	v_add_f32_e32 v17, v227, v229
	v_mfma_f32_32x32x16_bf16 v[18:33], v[4:7], v[114:117], v[18:33]
	v_mfma_f32_32x32x16_bf16 v[18:33], v[8:11], v[118:121], v[18:33]
	v_mfma_f32_32x32x16_bf16 v[18:33], v[12:15], v[122:125], v[18:33]
	v_mfma_f32_32x32x16_bf16 v[18:33], v[178:181], v[126:129], v[18:33]
	s_add_i32 s92, s68, 0x2000
	s_cmp_lg_u32 s68, 0x4000
	s_cselect_b32 s66, s92, 0
	s_addk_i32 s89, 0x80
	v_add_f32_e32 v227, v17, v16
	v_add_u32_e32 v3, 0xfffffe00, v3
	s_add_u32 s90, s90, 0x8000
	s_addc_u32 s91, s91, 0
	s_add_u32 s0, s0, 0x4000
	s_addc_u32 s1, s1, 0
	s_cmp_lt_i32 s62, s60
	s_cbranch_scc0 .LBB0_403
	s_mov_b32 s67, s86
	s_mov_b32 s2, s68
	s_mov_b32 s86, s66
	s_branch .LBB0_356

; #define SBAR() __builtin_amdgcn_sched_barrier(0)
; #define TLD(T, U, g) do { _Pragma("unroll") for (int j = 0; j < 4; ++j) { const int r_ = 4 * (g) + j, c_ = (r_ & 3) + 8 * (r_ >> 2); T[j] = *(const float*)(tabp + 4 * (59 - c_)); U[j] = *(const float*)(tabp + 4 * (59 - c_ - 32)); } } while (0)
; #define TAD(T, U, g) do { _Pragma("unroll") for (int j = 0; j < 4; ++j) { const int r_ = 4 * (g) + j; asm volatile("v_add_f32 %0, %0, %1" : "+v"(x0[r_]) : "v"(T[j])); asm volatile("v_add_f32 %0, %0, %1" : "+v"(x1[r_]) : "v"(U[j])); } } while (0)
; template <int VAR> ...
;     ...
;     if (near) {
;         float tA[4], uA[4], tB[4], uB[4];
;     ...
;         TLD(tA, uA, 0); SBAR(); TLD(tB, uB, 1); SBAR();
;         asm volatile("s_nop 15\n\ts_nop 7" : "+v"(x0), "+v"(x1));
;         TAD(tA, uA, 0); SBAR(); TLD(tA, uA, 2); SBAR(); TAD(tB, uB, 1); SBAR(); TLD(tB, uB, 3); SBAR(); TAD(tA, uA, 2); SBAR(); TAD(tB, uB, 3);
;     ...
;     } else if (__builtin_expect(shift != 0.f, 0)) {
.Lp2s_disp1:
	s_sub_i32 s92, s89, 64
	s_cmp_le_i32 s92, s85
	s_cbranch_scc1 .Lp2t_shift1

; __global__ void __launch_bounds__(NWAVES * 64, 2) mega_fwd(Args args) {
;     extern __shared__ __attribute__((aligned(16))) unsigned char lds[];
	.amdhsa_kernel _Z8mega_fwd4Args
		.amdhsa_group_segment_fixed_size 0
		.amdhsa_private_segment_fixed_size 0
		.amdhsa_kernarg_size 408
		.amdhsa_user_sgpr_count 2
		.amdhsa_user_sgpr_dispatch_ptr 0
		.amdhsa_user_sgpr_queue_ptr 0
		.amdhsa_user_sgpr_kernarg_segment_ptr 1
		.amdhsa_user_sgpr_dispatch_id 0
		.amdhsa_user_sgpr_kernarg_preload_length 0
		.amdhsa_user_sgpr_kernarg_preload_offset 0
		.amdhsa_user_sgpr_private_segment_size 0
		.amdhsa_uses_dynamic_stack 0
		.amdhsa_enable_private_segment 0
		.amdhsa_system_sgpr_workgroup_id_x 1
		.amdhsa_system_sgpr_workgroup_id_y 0
		.amdhsa_system_sgpr_workgroup_id_z 0
		.amdhsa_system_sgpr_workgroup_info 0
		.amdhsa_system_vgpr_workitem_id 0
		.amdhsa_next_free_vgpr 244
		.amdhsa_next_free_sgpr 102
		.amdhsa_accum_offset 244
		.amdhsa_reserve_vcc 1
		.amdhsa_float_round_mode_32 0
		.amdhsa_float_round_mode_16_64 0
		.amdhsa_float_denorm_mode_32 3
		.amdhsa_float_denorm_mode_16_64 3
		.amdhsa_dx10_clamp 1
		.amdhsa_ieee_mode 1
		.amdhsa_fp16_overflow 0
		.amdhsa_tg_split 0
		.amdhsa_exception_fp_ieee_invalid_op 0
		.amdhsa_exception_fp_denorm_src 0
		.amdhsa_exception_fp_ieee_div_zero 0
		.amdhsa_exception_fp_ieee_overflow 0
		.amdhsa_exception_fp_ieee_underflow 0
		.amdhsa_exception_fp_ieee_inexact 0
		.amdhsa_exception_int_div_zero 0
	.end_amdhsa_kernel

; __global__ void __launch_bounds__(NWAVES * 64, 2) mega_fwd(Args args) {
;     extern __shared__ __attribute__((aligned(16))) unsigned char lds[];
amdhsa.kernels:
  - .agpr_count:     0
    .args:
      - .offset:         0
        .size:           152
        .value_kind:     by_value
      - .offset:         152
        .size:           4
        .value_kind:     hidden_block_count_x
      - .offset:         156
        .size:           4
        .value_kind:     hidden_block_count_y
      - .offset:         160
        .size:           4
        .value_kind:     hidden_block_count_z
      - .offset:         164
        .size:           2
        .value_kind:     hidden_group_size_x
      - .offset:         166
        .size:           2
        .value_kind:     hidden_group_size_y
      - .offset:         168
        .size:           2
        .value_kind:     hidden_group_size_z
      - .offset:         170
        .size:           2
        .value_kind:     hidden_remainder_x
      - .offset:         172
        .size:           2
        .value_kind:     hidden_remainder_y
      - .offset:         174
        .size:           2
        .value_kind:     hidden_remainder_z
      - .offset:         192
        .size:           8
        .value_kind:     hidden_global_offset_x
      - .offset:         200
        .size:           8
        .value_kind:     hidden_global_offset_y
      - .offset:         208
        .size:           8
        .value_kind:     hidden_global_offset_z
      - .offset:         216
        .size:           2
        .value_kind:     hidden_grid_dims
      - .offset:         272
        .size:           4
        .value_kind:     hidden_dynamic_lds_size
    .group_segment_fixed_size: 0
    .kernarg_segment_align: 8
    .kernarg_segment_size: 408
    .language:       OpenCL C
    .language_version:
      - 2
      - 0
    .max_flat_workgroup_size: 512
    .name:           _Z8mega_fwd4Args
    .private_segment_fixed_size: 0
    .sgpr_count:     108
    .sgpr_spill_count: 23
    .symbol:         _Z8mega_fwd4Args.kd
    .uniform_work_group_size: 1
    .uses_dynamic_stack: false
    .vgpr_count:     244
    .vgpr_spill_count: 0
    .wavefront_size: 64
